# post phase rows: row-invariant parameter vectors loaded once before the row loop, GDN-half row data loaded with the RWKV half at the top of the row (one far round trip per row instead of two far + thr
# speedup vs baseline: 1.0093x; 1.0093x over previous
.LBB0_802:
	s_and_b64 vcc, exec, s[6:7]
	v_writelane_b32 v250, s81, 5
	s_cbranch_vccz .LBB0_806
	s_mov_b32 s14, 18
	s_mov_b32 s8, 19
	s_mov_b32 s6, 20
	s_mov_b32 s2, 24
	s_cmpk_gt_i32 s18, 0x21ff
	s_cbranch_scc1 .LBB0_806
	s_ashr_i32 s15, s14, 31
	s_lshl_b64 s[0:1], s[14:15], 3
	s_add_u32 s0, s48, s0
	s_addc_u32 s1, s49, s1
	s_ashr_i32 s9, s8, 31
	s_lshl_b64 s[4:5], s[8:9], 3
	s_add_u32 s4, s48, s4
	s_addc_u32 s5, s49, s5
	s_ashr_i32 s7, s6, 31
	s_lshl_b64 s[6:7], s[6:7], 3
	s_add_u32 s6, s48, s6
	s_addc_u32 s7, s49, s7
	s_ashr_i32 s3, s2, 31
	s_lshl_b64 s[2:3], s[2:3], 3
	s_add_u32 s2, s48, s2
	s_addc_u32 s3, s49, s3
	s_load_dwordx2 s[2:3], s[2:3], 0x0
	s_nop 0
	s_load_dwordx2 s[0:1], s[0:1], 0x0
	s_nop 0
	s_load_dwordx2 s[4:5], s[4:5], 0x0
	s_nop 0
	s_load_dwordx2 s[6:7], s[6:7], 0x0
	s_lshl_b64 s[8:9], s[12:13], 2
	s_waitcnt lgkmcnt(0)
	s_add_u32 s2, s2, s8
	s_addc_u32 s3, s3, s9
	v_readlane_b32 s8, v251, 10
	v_readlane_b32 s9, v251, 11
	s_lshl_b64 s[8:9], s[8:9], 2
	s_add_u32 s6, s6, s8
	s_addc_u32 s7, s7, s9
	s_add_u32 s4, s4, s8
	s_addc_u32 s5, s5, s9
	s_add_u32 s0, s0, s8
	s_addc_u32 s1, s1, s9
	s_waitcnt vmcnt(0)
	v_lshlrev_b32_e32 v2, 4, v138
	v_mov_b32_e32 v3, v1
	v_lshl_add_u64 v[62:63], s[4:5], 0, v[2:3]
	v_lshl_add_u64 v[64:65], s[6:7], 0, v[2:3]
	v_lshl_add_u64 v[66:67], s[0:1], 0, v[2:3]
	v_and_b32_e32 v2, 0x1f0, v2
	v_lshl_add_u64 v[68:69], s[2:3], 0, v[2:3]
	v_and_b32_e32 v2, 64, v206
	v_xor_b32_e32 v0, 16, v206
	v_add_u32_e32 v2, 64, v2
	v_cmp_lt_i32_e32 vcc, v0, v2
	s_ashr_i32 s19, s18, 31
	s_mul_hi_i32 s0, s18, 0x3c00
	s_mul_i32 s1, s18, 0x3c00
	v_lshlrev_b32_e32 v2, 3, v138
	v_cndmask_b32_e32 v0, v206, v0, vcc
	v_or_b32_e32 v70, s1, v2
	v_mov_b32_e32 v71, s0
	s_lshl_b64 s[0:1], s[18:19], 12
	v_lshlrev_b32_e32 v0, 2, v0
	v_or_b32_e32 v72, s0, v2
	v_mov_b32_e32 v73, s1
	v_lshl_or_b32 v74, v138, 4, s0
	v_mov_b32_e32 v75, s1
	s_mov_b32 s0, s18
	global_load_dwordx4 v[140:143], v[62:63], off
	global_load_dwordx4 v[144:147], v[64:65], off
	global_load_dwordx4 v[148:151], v[66:67], off
	global_load_dwordx4 v[152:155], v[62:63], off offset:1024
	global_load_dwordx4 v[156:159], v[64:65], off offset:1024
	global_load_dwordx4 v[160:163], v[66:67], off offset:1024
	global_load_dwordx4 v[164:167], v[62:63], off offset:2048
	global_load_dwordx4 v[168:171], v[64:65], off offset:2048
	global_load_dwordx4 v[172:175], v[66:67], off offset:2048
	global_load_dwordx4 v[176:179], v[62:63], off offset:3072
	global_load_dwordx4 v[180:183], v[64:65], off offset:3072
	global_load_dwordx4 v[184:187], v[66:67], off offset:3072
	global_load_dwordx4 v[188:191], v[68:69], off
.LBB0_805:
	v_lshl_add_u64 v[78:79], s[22:23], 0, v[74:75]
	v_add_co_u32_e32 v2, vcc, 0x35100000, v78
	s_mov_b32 s1, 0x1fd00000
	s_nop 0
	v_addc_co_u32_e32 v3, vcc, 0, v79, vcc
	global_load_dwordx4 v[80:83], v[2:3], off
	v_add_co_u32_e32 v4, vcc, 0x1db00000, v78
	s_add_i32 s0, s0, s50
	s_nop 0
	v_addc_co_u32_e32 v5, vcc, 0, v79, vcc
	v_add_co_u32_e32 v6, vcc, 0x21f00000, v78
	global_load_dwordx4 v[84:87], v[4:5], off
	s_nop 0
	v_addc_co_u32_e32 v7, vcc, 0, v79, vcc
	v_add_co_u32_e32 v8, vcc, 0x24100000, v78
	global_load_dwordx4 v[88:91], v[6:7], off
	s_nop 0
	v_addc_co_u32_e32 v9, vcc, 0, v79, vcc
	v_add_co_u32_e32 v76, vcc, 0x2a700000, v78
	global_load_dwordx4 v[92:95], v[8:9], off
	s_nop 0
	v_addc_co_u32_e32 v77, vcc, 0, v79, vcc
	global_load_dwordx4 v[96:99], v[76:77], off
	global_load_dwordx4 v[50:53], v[2:3], off offset:1024
	global_load_dwordx4 v[54:57], v[4:5], off offset:1024
	global_load_dwordx4 v[58:61], v[6:7], off offset:1024
	global_load_dwordx4 v[46:49], v[8:9], off offset:1024
	global_load_dwordx4 v[42:45], v[76:77], off offset:1024
	global_load_dwordx4 v[30:33], v[2:3], off offset:2048
	global_load_dwordx4 v[34:37], v[4:5], off offset:2048
	global_load_dwordx4 v[38:41], v[6:7], off offset:2048
	global_load_dwordx4 v[26:29], v[8:9], off offset:2048
	global_load_dwordx4 v[22:25], v[76:77], off offset:2048
	global_load_dwordx4 v[10:13], v[2:3], off offset:3072
	global_load_dwordx4 v[14:17], v[4:5], off offset:3072
	global_load_dwordx4 v[18:21], v[6:7], off offset:3072
	s_nop 0
	global_load_dwordx4 v[6:9], v[8:9], off offset:3072
	s_nop 0
	global_load_dwordx4 v[2:5], v[76:77], off offset:3072
	v_add_co_u32_e32 v236, vcc, 0x37300000, v78
	s_nop 0
	v_addc_co_u32_e32 v237, vcc, 0, v79, vcc
	global_load_dwordx4 v[192:195], v[236:237], off
	global_load_dwordx4 v[196:199], v[236:237], off offset:1024
	global_load_dwordx4 v[220:223], v[236:237], off offset:2048
	global_load_dwordx4 v[224:227], v[236:237], off offset:3072
	v_lshl_add_u64 v[238:239], s[22:23], 0, v[70:71]
	v_add_co_u32_e32 v238, vcc, 0xdc03000, v238
	s_nop 0
	v_addc_co_u32_e32 v239, vcc, 0, v239, vcc
	global_load_dwordx2 v[228:229], v[238:239], off offset:512
	global_load_dwordx2 v[230:231], v[238:239], off offset:1024
	global_load_dwordx2 v[232:233], v[238:239], off offset:1536
	global_load_dwordx2 v[234:235], v[238:239], off offset:2048
	v_lshl_add_u64 v[74:75], v[74:75], 0, s[70:71]
	s_cmpk_gt_i32 s0, 0x21ff
	s_waitcnt vmcnt(8)
	v_mov_b64_e32 v[100:101], v[140:141]
	v_mov_b64_e32 v[102:103], v[142:143]
	v_mov_b64_e32 v[104:105], v[144:145]
	v_mov_b64_e32 v[106:107], v[146:147]
	v_mov_b64_e32 v[108:109], v[148:149]
	v_mov_b64_e32 v[110:111], v[150:151]
	v_mov_b32_e32 v76, v81
	v_mov_b32_e32 v77, v82
	v_mov_b32_e32 v112, v80
	v_mov_b32_e32 v113, v83
	v_pk_add_f32 v[76:77], v[76:77], v[112:113]
	v_pk_mul_f32 v[54:55], v[54:55], v[58:59]
	v_add_f32_e32 v76, v76, v77
	v_pk_mul_f32 v[56:57], v[56:57], v[60:61]
	v_pk_mul_f32 v[34:35], v[34:35], v[38:39]
	v_add_f32_dpp v76, v76, v76 quad_perm:[1,0,3,2] row_mask:0xf bank_mask:0xf bound_ctrl:1
	v_pk_mul_f32 v[84:85], v[84:85], v[88:89]
	v_pk_mul_f32 v[86:87], v[86:87], v[90:91]
	v_add_f32_dpp v76, v76, v76 quad_perm:[2,3,0,1] row_mask:0xf bank_mask:0xf bound_ctrl:1
	v_pk_mul_f32 v[36:37], v[36:37], v[40:41]
	v_pk_mul_f32 v[14:15], v[14:15], v[18:19]
	v_add_f32_dpp v76, v76, v76 row_half_mirror row_mask:0xf bank_mask:0xf bound_ctrl:1
	v_pk_mul_f32 v[16:17], v[16:17], v[20:21]
	v_pk_mul_f32 v[84:85], v[84:85], v[108:109]
	v_add_f32_dpp v112, v76, v76 row_ror:8 row_mask:0xf bank_mask:0xf bound_ctrl:1
	v_fmamk_f32 v81, v112, 0xbc800000, v81
	v_fmac_f32_e32 v80, 0xbc800000, v112
	v_fmamk_f32 v77, v112, 0xbc800000, v83
	v_fmamk_f32 v76, v112, 0xbc800000, v82
	v_pk_mul_f32 v[82:83], v[80:81], v[80:81]
	v_pk_fma_f32 v[84:85], v[86:87], v[110:111], v[84:85]
	v_pk_fma_f32 v[82:83], v[76:77], v[76:77], v[82:83]
	s_nop 0
	v_add_f32_e32 v82, v82, v83
	v_add_f32_e32 v83, v84, v85
	s_nop 0
	v_add_f32_dpp v82, v82, v82 quad_perm:[1,0,3,2] row_mask:0xf bank_mask:0xf bound_ctrl:1
	v_add_f32_dpp v83, v83, v83 quad_perm:[1,0,3,2] row_mask:0xf bank_mask:0xf bound_ctrl:1
	s_nop 0
	v_add_f32_dpp v82, v82, v82 quad_perm:[2,3,0,1] row_mask:0xf bank_mask:0xf bound_ctrl:1
	v_add_f32_dpp v83, v83, v83 quad_perm:[2,3,0,1] row_mask:0xf bank_mask:0xf bound_ctrl:1
	s_nop 0
	v_add_f32_dpp v82, v82, v82 row_half_mirror row_mask:0xf bank_mask:0xf bound_ctrl:1
	v_add_f32_dpp v83, v83, v83 row_half_mirror row_mask:0xf bank_mask:0xf bound_ctrl:1
	s_nop 0
	v_add_f32_dpp v82, v82, v82 row_ror:8 row_mask:0xf bank_mask:0xf bound_ctrl:1
	v_fmamk_f32 v82, v82, 0x3c800000, v204
	v_rsq_f32_e32 v82, v82
	v_add_f32_dpp v84, v83, v83 row_ror:8 row_mask:0xf bank_mask:0xf bound_ctrl:1
	v_pk_mul_f32 v[80:81], v[80:81], v[82:83] op_sel_hi:[1,0]
	s_nop 0
	v_pk_fma_f32 v[80:81], v[100:101], v[80:81], v[104:105]
	v_pk_mul_f32 v[76:77], v[76:77], v[82:83] op_sel_hi:[1,0]
	v_pk_fma_f32 v[80:81], v[92:93], v[84:85], v[80:81] op_sel_hi:[1,0,1]
	v_pk_fma_f32 v[76:77], v[102:103], v[76:77], v[106:107]
	v_pk_mul_f32 v[80:81], v[96:97], v[80:81]
	v_pk_fma_f32 v[76:77], v[94:95], v[84:85], v[76:77] op_sel_hi:[1,0,1]
	v_bfe_u32 v82, v80, 16, 1
	v_add3_u32 v80, v80, v82, s60
	v_bfe_u32 v82, v81, 16, 1
	v_pk_mul_f32 v[76:77], v[98:99], v[76:77]
	v_lshrrev_b32_e32 v80, 16, v80
	v_add3_u32 v81, v81, v82, s60
	v_and_or_b32 v80, v81, s33, v80
	v_bfe_u32 v81, v76, 16, 1
	v_add3_u32 v76, v76, v81, s60
	v_bfe_u32 v81, v77, 16, 1
	v_lshrrev_b32_e32 v76, 16, v76
	v_add3_u32 v77, v77, v81, s60
	v_and_or_b32 v81, v77, s33, v76
	v_lshl_add_u64 v[76:77], s[22:23], 0, v[72:73]
	v_add_co_u32_e32 v76, vcc, s1, v76
	v_mov_b32_e32 v92, v51
	s_nop 0
	v_addc_co_u32_e32 v77, vcc, 0, v77, vcc
	global_store_dwordx2 v[76:77], v[80:81], off
	v_mov_b64_e32 v[80:81], v[152:153]
	v_mov_b64_e32 v[82:83], v[154:155]
	s_nop 0
	v_mov_b64_e32 v[84:85], v[156:157]
	v_mov_b64_e32 v[86:87], v[158:159]
	v_mov_b64_e32 v[88:89], v[160:161]
	v_mov_b64_e32 v[90:91], v[162:163]
	v_mov_b32_e32 v93, v52
	v_mov_b32_e32 v94, v50
	v_mov_b32_e32 v95, v53
	v_pk_add_f32 v[92:93], v[92:93], v[94:95]
	s_mov_b32 s1, 0x37300000
	v_add_f32_e32 v92, v92, v93
	v_lshl_add_u64 v[72:73], v[72:73], 0, s[70:71]
	s_nop 0
	v_pk_mul_f32 v[54:55], v[54:55], v[88:89]
	v_add_f32_dpp v92, v92, v92 quad_perm:[1,0,3,2] row_mask:0xf bank_mask:0xf bound_ctrl:1
	v_pk_fma_f32 v[54:55], v[56:57], v[90:91], v[54:55]
	v_mov_b32_e32 v56, v30
	v_add_f32_dpp v92, v92, v92 quad_perm:[2,3,0,1] row_mask:0xf bank_mask:0xf bound_ctrl:1
	v_add_f32_e32 v54, v54, v55
	v_mov_b32_e32 v57, v33
	v_add_f32_dpp v92, v92, v92 row_half_mirror row_mask:0xf bank_mask:0xf bound_ctrl:1
	v_add_f32_dpp v54, v54, v54 quad_perm:[1,0,3,2] row_mask:0xf bank_mask:0xf bound_ctrl:1
	s_nop 0
	v_add_f32_dpp v92, v92, v92 row_ror:8 row_mask:0xf bank_mask:0xf bound_ctrl:1
	v_fmamk_f32 v51, v92, 0xbc800000, v51
	v_fmac_f32_e32 v50, 0xbc800000, v92
	v_fmamk_f32 v53, v92, 0xbc800000, v53
	v_fmamk_f32 v52, v92, 0xbc800000, v52
	v_pk_mul_f32 v[92:93], v[50:51], v[50:51]
	v_add_f32_dpp v54, v54, v54 quad_perm:[2,3,0,1] row_mask:0xf bank_mask:0xf bound_ctrl:1
	v_pk_fma_f32 v[92:93], v[52:53], v[52:53], v[92:93]
	s_nop 0
	v_add_f32_e32 v92, v92, v93
	v_add_f32_dpp v54, v54, v54 row_half_mirror row_mask:0xf bank_mask:0xf bound_ctrl:1
	s_nop 0
	v_add_f32_dpp v92, v92, v92 quad_perm:[1,0,3,2] row_mask:0xf bank_mask:0xf bound_ctrl:1
	v_add_f32_dpp v54, v54, v54 row_ror:8 row_mask:0xf bank_mask:0xf bound_ctrl:1
	s_nop 0
	v_add_f32_dpp v92, v92, v92 quad_perm:[2,3,0,1] row_mask:0xf bank_mask:0xf bound_ctrl:1
	s_nop 1
	v_add_f32_dpp v92, v92, v92 row_half_mirror row_mask:0xf bank_mask:0xf bound_ctrl:1
	s_nop 1
	v_add_f32_dpp v92, v92, v92 row_ror:8 row_mask:0xf bank_mask:0xf bound_ctrl:1
	v_fmamk_f32 v92, v92, 0x3c800000, v204
	v_rsq_f32_e32 v92, v92
	s_nop 0
	v_pk_mul_f32 v[50:51], v[50:51], v[92:93] op_sel_hi:[1,0]
	s_nop 0
	v_pk_fma_f32 v[50:51], v[80:81], v[50:51], v[84:85]
	v_pk_mul_f32 v[52:53], v[52:53], v[92:93] op_sel_hi:[1,0]
	v_pk_fma_f32 v[46:47], v[46:47], v[54:55], v[50:51] op_sel_hi:[1,0,1]
	v_pk_fma_f32 v[52:53], v[82:83], v[52:53], v[86:87]
	v_pk_mul_f32 v[42:43], v[42:43], v[46:47]
	v_pk_fma_f32 v[48:49], v[48:49], v[54:55], v[52:53] op_sel_hi:[1,0,1]
	v_bfe_u32 v46, v42, 16, 1
	v_add3_u32 v42, v42, v46, s60
	v_bfe_u32 v46, v43, 16, 1
	v_pk_mul_f32 v[44:45], v[44:45], v[48:49]
	v_lshrrev_b32_e32 v42, 16, v42
	v_add3_u32 v43, v43, v46, s60
	v_and_or_b32 v42, v43, s33, v42
	v_bfe_u32 v43, v44, 16, 1
	v_add3_u32 v43, v44, v43, s60
	v_bfe_u32 v44, v45, 16, 1
	v_lshrrev_b32_e32 v43, 16, v43
	v_add3_u32 v44, v45, v44, s60
	v_and_or_b32 v43, v44, s33, v43
	global_store_dwordx2 v[76:77], v[42:43], off offset:512
	v_mov_b64_e32 v[42:43], v[164:165]
	v_mov_b64_e32 v[44:45], v[166:167]
	s_nop 0
	v_mov_b64_e32 v[46:47], v[168:169]
	v_mov_b64_e32 v[48:49], v[170:171]
	v_mov_b64_e32 v[50:51], v[172:173]
	v_mov_b64_e32 v[52:53], v[174:175]
	v_mov_b32_e32 v54, v31
	v_mov_b32_e32 v55, v32
	v_pk_add_f32 v[54:55], v[54:55], v[56:57]
	s_nop 0
	v_pk_mul_f32 v[34:35], v[34:35], v[50:51]
	v_add_f32_e32 v54, v54, v55
	v_pk_fma_f32 v[34:35], v[36:37], v[52:53], v[34:35]
	v_mov_b32_e32 v36, v10
	v_add_f32_dpp v54, v54, v54 quad_perm:[1,0,3,2] row_mask:0xf bank_mask:0xf bound_ctrl:1
	v_add_f32_e32 v34, v34, v35
	v_mov_b32_e32 v37, v13
	v_add_f32_dpp v54, v54, v54 quad_perm:[2,3,0,1] row_mask:0xf bank_mask:0xf bound_ctrl:1
	v_add_f32_dpp v34, v34, v34 quad_perm:[1,0,3,2] row_mask:0xf bank_mask:0xf bound_ctrl:1
	s_nop 0
	v_add_f32_dpp v54, v54, v54 row_half_mirror row_mask:0xf bank_mask:0xf bound_ctrl:1
	v_add_f32_dpp v34, v34, v34 quad_perm:[2,3,0,1] row_mask:0xf bank_mask:0xf bound_ctrl:1
	s_nop 0
	v_add_f32_dpp v54, v54, v54 row_ror:8 row_mask:0xf bank_mask:0xf bound_ctrl:1
	v_fmamk_f32 v31, v54, 0xbc800000, v31
	v_fmac_f32_e32 v30, 0xbc800000, v54
	v_fmamk_f32 v33, v54, 0xbc800000, v33
	v_fmamk_f32 v32, v54, 0xbc800000, v32
	v_pk_mul_f32 v[54:55], v[30:31], v[30:31]
	v_add_f32_dpp v34, v34, v34 row_half_mirror row_mask:0xf bank_mask:0xf bound_ctrl:1
	v_pk_fma_f32 v[54:55], v[32:33], v[32:33], v[54:55]
	s_nop 0
	v_add_f32_e32 v54, v54, v55
	v_add_f32_dpp v34, v34, v34 row_ror:8 row_mask:0xf bank_mask:0xf bound_ctrl:1
	s_nop 0
	v_add_f32_dpp v54, v54, v54 quad_perm:[1,0,3,2] row_mask:0xf bank_mask:0xf bound_ctrl:1
	s_nop 1
	v_add_f32_dpp v54, v54, v54 quad_perm:[2,3,0,1] row_mask:0xf bank_mask:0xf bound_ctrl:1
	s_nop 1
	v_add_f32_dpp v54, v54, v54 row_half_mirror row_mask:0xf bank_mask:0xf bound_ctrl:1
	s_nop 1
	v_add_f32_dpp v54, v54, v54 row_ror:8 row_mask:0xf bank_mask:0xf bound_ctrl:1
	v_fmamk_f32 v54, v54, 0x3c800000, v204
	v_rsq_f32_e32 v54, v54
	s_nop 0
	v_pk_mul_f32 v[30:31], v[30:31], v[54:55] op_sel_hi:[1,0]
	s_nop 0
	v_pk_fma_f32 v[30:31], v[42:43], v[30:31], v[46:47]
	v_pk_mul_f32 v[32:33], v[32:33], v[54:55] op_sel_hi:[1,0]
	v_pk_fma_f32 v[26:27], v[26:27], v[34:35], v[30:31] op_sel_hi:[1,0,1]
	v_pk_fma_f32 v[32:33], v[44:45], v[32:33], v[48:49]
	v_pk_mul_f32 v[22:23], v[22:23], v[26:27]
	v_pk_fma_f32 v[28:29], v[28:29], v[34:35], v[32:33] op_sel_hi:[1,0,1]
	v_bfe_u32 v26, v22, 16, 1
	v_add3_u32 v22, v22, v26, s60
	v_bfe_u32 v26, v23, 16, 1
	v_pk_mul_f32 v[24:25], v[24:25], v[28:29]
	v_lshrrev_b32_e32 v22, 16, v22
	v_add3_u32 v23, v23, v26, s60
	v_and_or_b32 v22, v23, s33, v22
	v_bfe_u32 v23, v24, 16, 1
	v_add3_u32 v23, v24, v23, s60
	v_bfe_u32 v24, v25, 16, 1
	v_lshrrev_b32_e32 v23, 16, v23
	v_add3_u32 v24, v25, v24, s60
	v_and_or_b32 v23, v24, s33, v23
	global_store_dwordx2 v[76:77], v[22:23], off offset:1024
	v_mov_b64_e32 v[22:23], v[176:177]
	v_mov_b64_e32 v[24:25], v[178:179]
	s_nop 0
	v_mov_b64_e32 v[26:27], v[180:181]
	v_mov_b64_e32 v[28:29], v[182:183]
	v_mov_b64_e32 v[30:31], v[184:185]
	v_mov_b64_e32 v[32:33], v[186:187]
	v_mov_b32_e32 v34, v11
	v_mov_b32_e32 v35, v12
	v_pk_add_f32 v[34:35], v[34:35], v[36:37]
	s_nop 0
	v_pk_mul_f32 v[14:15], v[14:15], v[30:31]
	v_add_f32_e32 v34, v34, v35
	v_pk_fma_f32 v[14:15], v[16:17], v[32:33], v[14:15]
	s_nop 0
	v_add_f32_dpp v34, v34, v34 quad_perm:[1,0,3,2] row_mask:0xf bank_mask:0xf bound_ctrl:1
	v_add_f32_e32 v14, v14, v15
	s_nop 0
	v_add_f32_dpp v34, v34, v34 quad_perm:[2,3,0,1] row_mask:0xf bank_mask:0xf bound_ctrl:1
	v_add_f32_dpp v14, v14, v14 quad_perm:[1,0,3,2] row_mask:0xf bank_mask:0xf bound_ctrl:1
	s_nop 0
	v_add_f32_dpp v34, v34, v34 row_half_mirror row_mask:0xf bank_mask:0xf bound_ctrl:1
	v_add_f32_dpp v14, v14, v14 quad_perm:[2,3,0,1] row_mask:0xf bank_mask:0xf bound_ctrl:1
	s_nop 0
	v_add_f32_dpp v34, v34, v34 row_ror:8 row_mask:0xf bank_mask:0xf bound_ctrl:1
	v_fmamk_f32 v11, v34, 0xbc800000, v11
	v_fmac_f32_e32 v10, 0xbc800000, v34
	v_fmamk_f32 v13, v34, 0xbc800000, v13
	v_fmamk_f32 v12, v34, 0xbc800000, v12
	v_pk_mul_f32 v[34:35], v[10:11], v[10:11]
	v_add_f32_dpp v14, v14, v14 row_half_mirror row_mask:0xf bank_mask:0xf bound_ctrl:1
	v_pk_fma_f32 v[34:35], v[12:13], v[12:13], v[34:35]
	s_nop 0
	v_add_f32_e32 v34, v34, v35
	v_add_f32_dpp v14, v14, v14 row_ror:8 row_mask:0xf bank_mask:0xf bound_ctrl:1
	s_nop 0
	v_add_f32_dpp v34, v34, v34 quad_perm:[1,0,3,2] row_mask:0xf bank_mask:0xf bound_ctrl:1
	s_nop 1
	v_add_f32_dpp v34, v34, v34 quad_perm:[2,3,0,1] row_mask:0xf bank_mask:0xf bound_ctrl:1
	s_nop 1
	v_add_f32_dpp v34, v34, v34 row_half_mirror row_mask:0xf bank_mask:0xf bound_ctrl:1
	s_nop 1
	v_add_f32_dpp v34, v34, v34 row_ror:8 row_mask:0xf bank_mask:0xf bound_ctrl:1
	v_fmamk_f32 v34, v34, 0x3c800000, v204
	v_rsq_f32_e32 v34, v34
	s_nop 0
	v_pk_mul_f32 v[10:11], v[10:11], v[34:35] op_sel_hi:[1,0]
	s_nop 0
	v_pk_fma_f32 v[10:11], v[22:23], v[10:11], v[26:27]
	v_pk_mul_f32 v[12:13], v[12:13], v[34:35] op_sel_hi:[1,0]
	v_pk_fma_f32 v[6:7], v[6:7], v[14:15], v[10:11] op_sel_hi:[1,0,1]
	v_pk_fma_f32 v[12:13], v[24:25], v[12:13], v[28:29]
	v_pk_mul_f32 v[2:3], v[2:3], v[6:7]
	v_pk_fma_f32 v[8:9], v[8:9], v[14:15], v[12:13] op_sel_hi:[1,0,1]
	v_bfe_u32 v6, v2, 16, 1
	v_add3_u32 v2, v2, v6, s60
	v_bfe_u32 v6, v3, 16, 1
	v_pk_mul_f32 v[4:5], v[4:5], v[8:9]
	v_lshrrev_b32_e32 v2, 16, v2
	v_add3_u32 v3, v3, v6, s60
	v_and_or_b32 v2, v3, s33, v2
	v_bfe_u32 v3, v4, 16, 1
	v_add3_u32 v3, v4, v3, s60
	v_bfe_u32 v4, v5, 16, 1
	v_lshrrev_b32_e32 v3, 16, v3
	v_add3_u32 v4, v5, v4, s60
	v_and_or_b32 v3, v4, s33, v3
	v_add_co_u32_e32 v6, vcc, s1, v78
	global_store_dwordx2 v[76:77], v[2:3], off offset:1536
	s_nop 0
	v_addc_co_u32_e32 v7, vcc, 0, v79, vcc
	s_waitcnt vmcnt(4)
	v_mov_b64_e32 v[2:3], v[192:193]
	v_mov_b64_e32 v[4:5], v[194:195]
	v_lshl_add_u64 v[8:9], s[22:23], 0, v[70:71]
	s_mov_b32 s1, 0xdc03000
	v_add_co_u32_e32 v20, vcc, s1, v8
	v_lshl_add_u64 v[70:71], v[70:71], 0, s[84:85]
	s_nop 0
	v_addc_co_u32_e32 v21, vcc, 0, v9, vcc
	v_mov_b64_e32 v[24:25], v[228:229]
	v_mov_b64_e32 v[8:9], v[196:197]
	v_mov_b64_e32 v[10:11], v[198:199]
	v_mov_b64_e32 v[26:27], v[230:231]
	v_mov_b64_e32 v[12:13], v[220:221]
	v_mov_b64_e32 v[14:15], v[222:223]
	v_mov_b64_e32 v[28:29], v[232:233]
	v_mov_b64_e32 v[16:17], v[224:225]
	v_mov_b64_e32 v[18:19], v[226:227]
	s_nop 0
	v_mov_b64_e32 v[6:7], v[234:235]
	s_nop 0
	v_mov_b64_e32 v[20:21], v[188:189]
	v_mov_b64_e32 v[22:23], v[190:191]
	s_nop 0
	v_pk_mul_f32 v[30:31], v[2:3], v[2:3]
	s_nop 0
	v_pk_fma_f32 v[30:31], v[4:5], v[4:5], v[30:31]
	s_nop 0
	v_lshlrev_b32_e32 v32, 16, v24
	v_add_f32_e32 v30, v30, v31
	v_lshlrev_b32_e32 v33, 16, v25
	v_and_b32_e32 v24, 0xffff0000, v24
	v_add_f32_dpp v30, v30, v30 quad_perm:[1,0,3,2] row_mask:0xf bank_mask:0xf bound_ctrl:1
	v_mov_b32_e32 v38, v2
	v_mul_f32_e32 v2, 0xbfb8aa3b, v33
	v_add_f32_dpp v30, v30, v30 quad_perm:[2,3,0,1] row_mask:0xf bank_mask:0xf bound_ctrl:1
	v_exp_f32_e32 v2, v2
	v_and_b32_e32 v25, 0xffff0000, v25
	v_add_f32_dpp v30, v30, v30 row_half_mirror row_mask:0xf bank_mask:0xf bound_ctrl:1
	v_mov_b32_e32 v39, v4
	v_add_f32_e32 v2, 1.0, v2
	v_add_f32_dpp v30, v30, v30 row_ror:8 row_mask:0xf bank_mask:0xf bound_ctrl:1
	ds_bpermute_b32 v31, v0, v30
	v_mov_b32_e32 v4, v3
	v_rcp_f32_e32 v35, v2
	s_nop 0
	v_mov_b32_e32 v41, v22
	v_mov_b32_e32 v22, v21
	s_waitcnt lgkmcnt(0)
	v_add_f32_e32 v30, v30, v31
	v_mul_f32_e32 v31, 0xbfb8aa3b, v32
	v_exp_f32_e32 v31, v31
	v_fmamk_f32 v30, v30, 0x3c000000, v205
	v_rsq_f32_e32 v30, v30
	v_mov_b32_e32 v40, v20
	v_add_f32_e32 v31, 1.0, v31
	v_rcp_f32_e32 v34, v31
	v_mul_f32_e32 v31, 0xbfb8aa3b, v24
	v_exp_f32_e32 v31, v31
	v_pk_mul_f32 v[32:33], v[34:35], v[32:33]
	v_add_f32_e32 v31, 1.0, v31
	v_pk_mul_f32 v[2:3], v[4:5], v[30:31] op_sel_hi:[1,0]
	v_mul_f32_e32 v4, 0xbfb8aa3b, v25
	v_exp_f32_e32 v4, v4
	v_rcp_f32_e32 v36, v31
	v_pk_mul_f32 v[38:39], v[38:39], v[30:31] op_sel_hi:[1,0]
	v_pk_mul_f32 v[2:3], v[22:23], v[2:3]
	v_add_f32_e32 v4, 1.0, v4
	v_rcp_f32_e32 v37, v4
	v_pk_mul_f32 v[38:39], v[40:41], v[38:39]
	v_mov_b32_e32 v30, v8
	v_pk_mul_f32 v[32:33], v[32:33], v[38:39]
	v_pk_mul_f32 v[4:5], v[36:37], v[24:25]
	v_mov_b32_e32 v31, v10
	v_pk_mul_f32 v[2:3], v[4:5], v[2:3]
	v_and_b32_sdwa v4, v33, v202 dst_sel:DWORD dst_unused:UNUSED_PAD src0_sel:WORD_1 src1_sel:DWORD
	v_and_b32_sdwa v20, v3, v202 dst_sel:DWORD dst_unused:UNUSED_PAD src0_sel:WORD_1 src1_sel:DWORD
	v_and_b32_sdwa v21, v2, v202 dst_sel:DWORD dst_unused:UNUSED_PAD src0_sel:WORD_1 src1_sel:DWORD
	v_and_b32_sdwa v5, v32, v202 dst_sel:DWORD dst_unused:UNUSED_PAD src0_sel:WORD_1 src1_sel:DWORD
	v_add3_u32 v3, v3, v20, s60
	v_add3_u32 v2, v2, v21, s60
	v_add3_u32 v5, v32, v5, s60
	v_add3_u32 v4, v33, v4, s60
	v_and_b32_e32 v3, 0xffff0000, v3
	v_and_b32_e32 v2, 0xffff0000, v2
	v_or_b32_sdwa v3, v3, v4 dst_sel:DWORD dst_unused:UNUSED_PAD src0_sel:DWORD src1_sel:WORD_1
	v_or_b32_sdwa v2, v2, v5 dst_sel:DWORD dst_unused:UNUSED_PAD src0_sel:DWORD src1_sel:WORD_1
	global_store_dwordx2 v[76:77], v[2:3], off offset:2048
	v_pk_mul_f32 v[2:3], v[8:9], v[8:9]
	v_lshlrev_b32_e32 v4, 16, v26
	v_pk_fma_f32 v[2:3], v[10:11], v[10:11], v[2:3]
	v_and_b32_e32 v20, 0xffff0000, v26
	v_add_f32_e32 v2, v2, v3
	v_lshlrev_b32_e32 v5, 16, v27
	v_and_b32_e32 v21, 0xffff0000, v27
	v_add_f32_dpp v2, v2, v2 quad_perm:[1,0,3,2] row_mask:0xf bank_mask:0xf bound_ctrl:1
	v_mul_f32_e32 v8, 0xbfb8aa3b, v21
	v_exp_f32_e32 v8, v8
	v_add_f32_dpp v2, v2, v2 quad_perm:[2,3,0,1] row_mask:0xf bank_mask:0xf bound_ctrl:1
	v_mov_b32_e32 v10, v9
	v_add_f32_e32 v8, 1.0, v8
	v_add_f32_dpp v2, v2, v2 row_half_mirror row_mask:0xf bank_mask:0xf bound_ctrl:1
	v_rcp_f32_e32 v27, v8
	s_nop 0
	v_add_f32_dpp v2, v2, v2 row_ror:8 row_mask:0xf bank_mask:0xf bound_ctrl:1
	ds_bpermute_b32 v3, v0, v2
	s_waitcnt lgkmcnt(0)
	v_add_f32_e32 v2, v2, v3
	v_mul_f32_e32 v3, 0xbfb8aa3b, v4
	v_exp_f32_e32 v3, v3
	v_fmamk_f32 v2, v2, 0x3c000000, v205
	v_rsq_f32_e32 v2, v2
	v_add_f32_e32 v3, 1.0, v3
	v_rcp_f32_e32 v24, v3
	v_mul_f32_e32 v3, 0xbfb8aa3b, v20
	v_exp_f32_e32 v3, v3
	s_nop 0
	v_add_f32_e32 v3, 1.0, v3
	v_rcp_f32_e32 v26, v3
	v_pk_mul_f32 v[30:31], v[30:31], v[2:3] op_sel_hi:[1,0]
	v_mul_f32_e32 v3, 0xbfb8aa3b, v5
	v_exp_f32_e32 v3, v3
	v_pk_mul_f32 v[30:31], v[40:41], v[30:31]
	v_pk_mul_f32 v[8:9], v[26:27], v[20:21]
	v_add_f32_e32 v3, 1.0, v3
	v_rcp_f32_e32 v25, v3
	v_pk_mul_f32 v[2:3], v[10:11], v[2:3] op_sel_hi:[1,0]
	v_pk_mul_f32 v[4:5], v[24:25], v[4:5]
	s_nop 0
	v_pk_mul_f32 v[4:5], v[4:5], v[30:31]
	v_pk_mul_f32 v[2:3], v[22:23], v[2:3]
	v_mov_b32_e32 v24, v12
	v_pk_mul_f32 v[2:3], v[8:9], v[2:3]
	v_and_b32_sdwa v8, v5, v202 dst_sel:DWORD dst_unused:UNUSED_PAD src0_sel:WORD_1 src1_sel:DWORD
	v_and_b32_sdwa v9, v4, v202 dst_sel:DWORD dst_unused:UNUSED_PAD src0_sel:WORD_1 src1_sel:DWORD
	v_add3_u32 v4, v4, v9, s60
	v_add3_u32 v5, v5, v8, s60
	v_and_b32_sdwa v8, v3, v202 dst_sel:DWORD dst_unused:UNUSED_PAD src0_sel:WORD_1 src1_sel:DWORD
	v_and_b32_sdwa v9, v2, v202 dst_sel:DWORD dst_unused:UNUSED_PAD src0_sel:WORD_1 src1_sel:DWORD
	v_add3_u32 v3, v3, v8, s60
	v_add3_u32 v2, v2, v9, s60
	v_and_b32_e32 v3, 0xffff0000, v3
	v_and_b32_e32 v2, 0xffff0000, v2
	v_or_b32_sdwa v3, v3, v5 dst_sel:DWORD dst_unused:UNUSED_PAD src0_sel:DWORD src1_sel:WORD_1
	v_or_b32_sdwa v2, v2, v4 dst_sel:DWORD dst_unused:UNUSED_PAD src0_sel:DWORD src1_sel:WORD_1
	global_store_dwordx2 v[76:77], v[2:3], off offset:2560
	v_pk_mul_f32 v[2:3], v[12:13], v[12:13]
	v_lshlrev_b32_e32 v4, 16, v28
	v_pk_fma_f32 v[2:3], v[14:15], v[14:15], v[2:3]
	v_and_b32_e32 v8, 0xffff0000, v28
	v_add_f32_e32 v2, v2, v3
	v_lshlrev_b32_e32 v5, 16, v29
	v_mov_b32_e32 v25, v14
	v_add_f32_dpp v2, v2, v2 quad_perm:[1,0,3,2] row_mask:0xf bank_mask:0xf bound_ctrl:1
	v_and_b32_e32 v9, 0xffff0000, v29
	v_mov_b32_e32 v14, v13
	v_add_f32_dpp v2, v2, v2 quad_perm:[2,3,0,1] row_mask:0xf bank_mask:0xf bound_ctrl:1
	v_mov_b32_e32 v12, v16
	v_mov_b32_e32 v13, v18
	v_add_f32_dpp v2, v2, v2 row_half_mirror row_mask:0xf bank_mask:0xf bound_ctrl:1
	s_nop 1
	v_add_f32_dpp v2, v2, v2 row_ror:8 row_mask:0xf bank_mask:0xf bound_ctrl:1
	ds_bpermute_b32 v3, v0, v2
	s_waitcnt lgkmcnt(0)
	v_add_f32_e32 v2, v2, v3
	v_mul_f32_e32 v3, 0xbfb8aa3b, v4
	v_exp_f32_e32 v3, v3
	v_fmamk_f32 v2, v2, 0x3c000000, v205
	v_rsq_f32_e32 v2, v2
	v_add_f32_e32 v3, 1.0, v3
	v_rcp_f32_e32 v10, v3
	v_mul_f32_e32 v3, 0xbfb8aa3b, v8
	v_exp_f32_e32 v3, v3
	s_nop 0
	v_add_f32_e32 v3, 1.0, v3
	v_rcp_f32_e32 v20, v3
	v_pk_mul_f32 v[24:25], v[24:25], v[2:3] op_sel_hi:[1,0]
	v_mul_f32_e32 v3, 0xbfb8aa3b, v5
	v_exp_f32_e32 v3, v3
	v_pk_mul_f32 v[24:25], v[40:41], v[24:25]
	v_add_f32_e32 v3, 1.0, v3
	v_rcp_f32_e32 v11, v3
	v_pk_mul_f32 v[2:3], v[14:15], v[2:3] op_sel_hi:[1,0]
	v_pk_mul_f32 v[4:5], v[10:11], v[4:5]
	v_mul_f32_e32 v10, 0xbfb8aa3b, v9
	v_exp_f32_e32 v10, v10
	v_pk_mul_f32 v[4:5], v[4:5], v[24:25]
	v_pk_mul_f32 v[2:3], v[22:23], v[2:3]
	v_add_f32_e32 v10, 1.0, v10
	v_rcp_f32_e32 v21, v10
	s_nop 0
	v_pk_mul_f32 v[8:9], v[20:21], v[8:9]
	s_nop 0
	v_pk_mul_f32 v[2:3], v[8:9], v[2:3]
	v_and_b32_sdwa v8, v5, v202 dst_sel:DWORD dst_unused:UNUSED_PAD src0_sel:WORD_1 src1_sel:DWORD
	v_and_b32_sdwa v9, v4, v202 dst_sel:DWORD dst_unused:UNUSED_PAD src0_sel:WORD_1 src1_sel:DWORD
	v_add3_u32 v4, v4, v9, s60
	v_add3_u32 v5, v5, v8, s60
	v_and_b32_sdwa v8, v3, v202 dst_sel:DWORD dst_unused:UNUSED_PAD src0_sel:WORD_1 src1_sel:DWORD
	v_and_b32_sdwa v9, v2, v202 dst_sel:DWORD dst_unused:UNUSED_PAD src0_sel:WORD_1 src1_sel:DWORD
	v_add3_u32 v3, v3, v8, s60
	v_add3_u32 v2, v2, v9, s60
	v_and_b32_e32 v3, 0xffff0000, v3
	v_and_b32_e32 v2, 0xffff0000, v2
	v_or_b32_sdwa v3, v3, v5 dst_sel:DWORD dst_unused:UNUSED_PAD src0_sel:DWORD src1_sel:WORD_1
	v_or_b32_sdwa v2, v2, v4 dst_sel:DWORD dst_unused:UNUSED_PAD src0_sel:DWORD src1_sel:WORD_1
	global_store_dwordx2 v[76:77], v[2:3], off offset:3072
	v_pk_mul_f32 v[2:3], v[16:17], v[16:17]
	v_lshlrev_b32_e32 v4, 16, v6
	v_pk_fma_f32 v[2:3], v[18:19], v[18:19], v[2:3]
	v_and_b32_e32 v6, 0xffff0000, v6
	v_add_f32_e32 v2, v2, v3
	v_lshlrev_b32_e32 v5, 16, v7
	v_and_b32_e32 v7, 0xffff0000, v7
	v_add_f32_dpp v2, v2, v2 quad_perm:[1,0,3,2] row_mask:0xf bank_mask:0xf bound_ctrl:1
	v_mov_b32_e32 v18, v17
	s_nop 0
	v_add_f32_dpp v2, v2, v2 quad_perm:[2,3,0,1] row_mask:0xf bank_mask:0xf bound_ctrl:1
	s_nop 1
	v_add_f32_dpp v2, v2, v2 row_half_mirror row_mask:0xf bank_mask:0xf bound_ctrl:1
	s_nop 1
	v_add_f32_dpp v2, v2, v2 row_ror:8 row_mask:0xf bank_mask:0xf bound_ctrl:1
	ds_bpermute_b32 v3, v0, v2
	s_waitcnt lgkmcnt(0)
	v_add_f32_e32 v2, v2, v3
	v_mul_f32_e32 v3, 0xbfb8aa3b, v4
	v_exp_f32_e32 v3, v3
	v_fmamk_f32 v2, v2, 0x3c000000, v205
	v_rsq_f32_e32 v2, v2
	v_add_f32_e32 v3, 1.0, v3
	v_rcp_f32_e32 v8, v3
	v_mul_f32_e32 v3, 0xbfb8aa3b, v6
	v_exp_f32_e32 v3, v3
	s_nop 0
	v_add_f32_e32 v3, 1.0, v3
	v_rcp_f32_e32 v10, v3
	v_pk_mul_f32 v[12:13], v[12:13], v[2:3] op_sel_hi:[1,0]
	v_mul_f32_e32 v3, 0xbfb8aa3b, v5
	v_exp_f32_e32 v3, v3
	v_pk_mul_f32 v[12:13], v[40:41], v[12:13]
	v_add_f32_e32 v3, 1.0, v3
	v_rcp_f32_e32 v9, v3
	v_pk_mul_f32 v[2:3], v[18:19], v[2:3] op_sel_hi:[1,0]
	v_pk_mul_f32 v[4:5], v[8:9], v[4:5]
	v_mul_f32_e32 v8, 0xbfb8aa3b, v7
	v_exp_f32_e32 v8, v8
	v_pk_mul_f32 v[4:5], v[4:5], v[12:13]
	v_pk_mul_f32 v[2:3], v[22:23], v[2:3]
	v_add_f32_e32 v8, 1.0, v8
	v_rcp_f32_e32 v11, v8
	s_nop 0
	v_pk_mul_f32 v[6:7], v[10:11], v[6:7]
	s_nop 0
	v_pk_mul_f32 v[2:3], v[6:7], v[2:3]
	v_and_b32_sdwa v6, v5, v202 dst_sel:DWORD dst_unused:UNUSED_PAD src0_sel:WORD_1 src1_sel:DWORD
	v_and_b32_sdwa v7, v4, v202 dst_sel:DWORD dst_unused:UNUSED_PAD src0_sel:WORD_1 src1_sel:DWORD
	v_add3_u32 v4, v4, v7, s60
	v_add3_u32 v5, v5, v6, s60
	v_and_b32_sdwa v6, v3, v202 dst_sel:DWORD dst_unused:UNUSED_PAD src0_sel:WORD_1 src1_sel:DWORD
	v_and_b32_sdwa v7, v2, v202 dst_sel:DWORD dst_unused:UNUSED_PAD src0_sel:WORD_1 src1_sel:DWORD
	v_add3_u32 v3, v3, v6, s60
	v_add3_u32 v2, v2, v7, s60
	v_and_b32_e32 v3, 0xffff0000, v3
	v_and_b32_e32 v2, 0xffff0000, v2
	v_or_b32_sdwa v3, v3, v5 dst_sel:DWORD dst_unused:UNUSED_PAD src0_sel:DWORD src1_sel:WORD_1
	v_or_b32_sdwa v2, v2, v4 dst_sel:DWORD dst_unused:UNUSED_PAD src0_sel:DWORD src1_sel:WORD_1
	global_store_dwordx2 v[76:77], v[2:3], off offset:3584
	s_cbranch_scc0 .LBB0_805
